# block 0 raises the zeroing flag after the workgroup barrier (race fix); no L2 writeback/invalidate in the init
# speedup vs baseline: 1.0017x; 1.0017x over previous
.LBB0_4:
	v_add_u32_e32 v1, 0x200, v1
	v_cmp_lt_u32_e32 vcc, s3, v1
	global_store_dword v[4:5], v3, off sc1
	s_or_b64 s[4:5], vcc, s[4:5]
	v_lshl_add_u64 v[4:5], v[4:5], 0, s[6:7]
	s_andn2_b64 exec, exec, s[4:5]
	s_cbranch_execnz .LBB0_4
	s_or_b64 exec, exec, s[4:5]
	s_waitcnt vmcnt(0)
.LBB0_6:
	s_cmpk_lt_i32 s2, 0x300
	s_mov_b64 s[8:9], s[0:1]
	v_mov_b32_e32 v1, v170
	s_cselect_b64 s[50:51], -1, 0
	s_cmpk_gt_i32 s2, 0x2ff
	s_waitcnt lgkmcnt(0)
	s_barrier
	s_cmp_lg_u32 s2, 0
	s_cbranch_scc1 .Lgs_noflag
	s_and_saveexec_b64 s[14:15], s[38:39]
	s_load_dwordx2 s[16:17], s[88:89], 0x58
	v_mov_b32_e32 v2, 0
	v_mov_b32_e32 v3, 1
	s_waitcnt lgkmcnt(0)
	global_atomic_add v2, v3, s[16:17] offset:32
	s_or_b64 exec, exec, s[14:15]
.Lgs_noflag:
	s_cmpk_gt_i32 s2, 0x2ff
	s_cbranch_scc1 .LBB0_17
	s_load_dwordx2 s[10:11], s[8:9], 0xe8
	s_load_dwordx2 s[12:13], s[8:9], 0x38
	v_lshlrev_b32_e32 v2, 5, v1
	s_movk_i32 s3, 0xa0
	v_and_b32_e32 v2, 0xfffffc00, v2
	v_cmp_gt_i32_e64 s[4:5], s3, v1
	v_and_b32_e32 v12, 31, v1
	v_cmp_lt_u32_e64 s[6:7], 31, v1
	v_add_u32_e32 v13, 0xfffffc00, v2
	v_lshl_add_u32 v14, v1, 2, 0
	v_mov_b32_e32 v3, 0
	s_mov_b32 s3, 0xbfb8aa3b
	s_mov_b32 s18, 0x42ce8ed0
	s_mov_b32 s19, 0xc2b17218
	s_movk_i32 s20, 0x6000
	s_mov_b32 s21, 0xc000
	s_mov_b32 s22, 0x12000
	s_mov_b32 s23, 0x18000
	s_mov_b32 s24, 0x1e000
	s_mov_b32 s25, 0x24000
	s_mov_b32 s26, 0x2a000
	v_mov_b32_e32 v15, 0x7f800000
	s_mov_b32 s27, s2
	s_mov_b32 s28, s2
